# as previous + the gate section no longer waits for the qkdv LDS writes (lgkmcnt(5))
# speedup vs baseline: 1.0011x; 1.0011x over previous
; __device__ __forceinline__ float bflo(unsigned u) { return __uint_as_float(u << 16); }
; __device__ __forceinline__ float bfhi(unsigned u) { return __uint_as_float(u & 0xffff0000u); }
; __device__ __forceinline__ float siluf_(float x) { return x * __builtin_amdgcn_rcpf(1.0f + __expf(-x)); }
; template <int N, int RS>
; __device__ __forceinline__ void convN(const bf16_t* rawb, const float (&w)[4][N], int tt, int off, float (&x)[N]) {
; #pragma unroll
;   for (int i = 0; i < N; ++i) x[i] = 0.f;
; #pragma unroll
;   for (int j = 0; j < 4; ++j) {
;     float xv[N];
;     if (N == 8) { const uint4 rv = *(const uint4*)(rawb + (tt + j) * RS + off); unpack8(rv, xv); }
;     else if (N == 4) { const uint2 rv = *(const uint2*)(rawb + (tt + j) * RS + off); xv[0] = bflo(rv.x); xv[1] = bfhi(rv.x); xv[2 % N] = bflo(rv.y); xv[3 % N] = bfhi(rv.y); }
;     else { const unsigned rv = *(const unsigned*)(rawb + (tt + j) * RS + off); xv[0] = bflo(rv); xv[1] = bfhi(rv); }
; #pragma unroll
;     for (int i = 0; i < N; ++i) x[i] += w[j][i] * xv[i];
;   }
;   if (N == 2) {
; #pragma unroll
;     for (int i = 0; i < N; ++i) asm volatile("" : "+v"(x[i]));
;   }
; #pragma unroll
;   for (int i = 0; i < N; ++i) x[i] = siluf_(x[i]);
; template <int MIX>
; __device__ __forceinline__ void scan_part(const Params& p, const int layer, const int smp, const int b0, const int bstep, const int bend, const int h, const int part, char* lds, const int tid) {
;     ...
;       if (valid) {
;         float xq[8], xk[8], xv[VN];
;         { float cwv[4][VN];
; #pragma unroll
;           for (int j = 0; j < 4; ++j)
; #pragma unroll
;             for (int i = 0; i < VN; ++i) cwv[j][i] = cwl[j * RS + 128 + sub * VN + i];
;           convN<VN, RS>(rawb, cwv, tt, 128 + sub * VN, xv); }
;         convN<8, RS>(rawb, cwq, tt, sub * 8, xq);
;         convN<8, RS>(rawb, cwk, tt, 64 + sub * 8, xk);
.Ld_top_done:
	s_and_saveexec_b64 s[50:51], s[42:43]
	s_cbranch_execz .LBB0_426
	v_add_u32_e32 v232, s23, v131
	v_lshlrev_b32_e32 v232, 2, v232
	ds_read_b32 v230, v232 offset:50880
	v_lshlrev_b32_e32 v231, 16, v133
	v_mul_f32_e32 v231, 0xbfb8aa3b, v231
	v_add_u32_e32 v2, v140, v138
	v_add_u32_e32 v0, 0x9200, v2
	v_add_u32_e32 v76, 0xbc00, v137
	v_exp_f32_e32 v231, v231
	ds_read2_b32 v[0:1], v0 offset0:64 offset1:136
	ds_read2_b64 v[76:79], v76 offset0:120 offset1:192
	v_add_u32_e32 v80, 0xc000, v137
	v_add_u32_e32 v2, 0x9400, v2
	v_add_f32_e32 v231, 1.0, v231
	ds_read2_b64 v[80:83], v80 offset0:136 offset1:208
	s_waitcnt lgkmcnt(2)
	v_lshlrev_b32_e32 v85, 16, v1
	v_lshlrev_b32_e32 v84, 16, v0
	v_rcp_f32_e32 v231, v231
	s_waitcnt lgkmcnt(1)
	v_mov_b32_e32 v86, v76
	v_mov_b32_e32 v87, v78
	v_pk_mul_f32 v[84:85], v[86:87], v[84:85]
	v_and_b32_e32 v1, 0xffff0000, v1
	v_add_f32_e32 v76, 0, v84
	v_add_f32_e32 v86, v76, v85
	ds_read2_b32 v[84:85], v2 offset0:80 offset1:152
	v_and_b32_e32 v0, 0xffff0000, v0
	v_mov_b32_e32 v78, v77
	v_pk_mul_f32 v[0:1], v[78:79], v[0:1]
	s_waitcnt lgkmcnt(1)
	v_mov_b32_e32 v76, v80
	v_add_f32_e32 v0, 0, v0
	v_add_f32_e32 v2, v0, v1
	s_waitcnt lgkmcnt(0)
	v_lshlrev_b32_e32 v1, 16, v85
	v_lshlrev_b32_e32 v0, 16, v84
	v_mov_b32_e32 v77, v82
	v_pk_mul_f32 v[0:1], v[76:77], v[0:1]
	v_and_b32_e32 v77, 0xffff0000, v85
	v_and_b32_e32 v76, 0xffff0000, v84
	v_mov_b32_e32 v82, v81
	v_add_f32_e32 v0, v86, v0
	v_pk_mul_f32 v[76:77], v[82:83], v[76:77]
	v_add_f32_e32 v0, v0, v1
	v_add_f32_e32 v1, v2, v76
	v_add_f32_e32 v1, v1, v77
	ds_read_b128 v[78:81], v151 offset:37376
	ds_read_b128 v[82:85], v151 offset:37504
	ds_read_b128 v[86:89], v151 offset:37664
	ds_read_b128 v[90:93], v151 offset:37952
	v_mul_f32_e32 v2, 0xbfb8aa3b, v0
	ds_read_b128 v[174:177], v151 offset:38240
	v_exp_f32_e32 v2, v2
	v_mul_f32_e32 v76, 0xbfb8aa3b, v1
	v_exp_f32_e32 v77, v76
	s_waitcnt lgkmcnt(4)
	v_lshlrev_b32_e32 v154, 16, v80
	v_and_b32_e32 v155, 0xffff0000, v80
	v_lshlrev_b32_e32 v94, 16, v78
	v_and_b32_e32 v95, 0xffff0000, v78
	v_lshlrev_b32_e32 v106, 16, v79
	v_and_b32_e32 v107, 0xffff0000, v79
	v_lshlrev_b32_e32 v178, 16, v81
	v_and_b32_e32 v179, 0xffff0000, v81
	ds_read_b128 v[78:81], v151 offset:37792
	s_waitcnt lgkmcnt(3)
	v_lshlrev_b32_e32 v180, 16, v86
	v_and_b32_e32 v181, 0xffff0000, v86
	v_lshlrev_b32_e32 v182, 16, v87
	v_and_b32_e32 v183, 0xffff0000, v87
	v_lshlrev_b32_e32 v184, 16, v88
	v_and_b32_e32 v185, 0xffff0000, v88
	v_lshlrev_b32_e32 v186, 16, v89
	v_and_b32_e32 v187, 0xffff0000, v89
	ds_read_b128 v[86:89], v151 offset:38080
	s_waitcnt lgkmcnt(3)
	v_lshlrev_b32_e32 v188, 16, v90
	v_and_b32_e32 v189, 0xffff0000, v90
	v_lshlrev_b32_e32 v190, 16, v91
	v_and_b32_e32 v191, 0xffff0000, v91
	v_lshlrev_b32_e32 v192, 16, v92
	v_and_b32_e32 v193, 0xffff0000, v92
	v_lshlrev_b32_e32 v194, 16, v93
	v_and_b32_e32 v195, 0xffff0000, v93
	ds_read_b128 v[90:93], v151 offset:38368
	s_waitcnt vmcnt(2)
	v_pk_fma_f32 v[154:155], v[4:5], v[154:155], 0 op_sel_hi:[1,1,0]
	v_add_f32_e32 v2, 1.0, v2
	s_waitcnt vmcnt(2)
	v_pk_fma_f32 v[154:155], v[12:13], v[184:185], v[154:155]
	s_waitcnt lgkmcnt(3)
	v_lshlrev_b32_e32 v198, 16, v176
	v_and_b32_e32 v199, 0xffff0000, v176
	s_waitcnt vmcnt(2)
	v_pk_fma_f32 v[154:155], v[20:21], v[192:193], v[154:155]
	v_rcp_f32_e32 v76, v2
	v_add_f32_e32 v2, 1.0, v77
	s_waitcnt vmcnt(2)
	v_pk_fma_f32 v[154:155], v[28:29], v[198:199], v[154:155]
	v_rcp_f32_e32 v77, v2
	v_mul_f32_e32 v2, 0xbfb8aa3b, v154
	v_lshlrev_b32_e32 v202, 16, v84
	v_and_b32_e32 v203, 0xffff0000, v84
	s_waitcnt lgkmcnt(0)
	v_lshlrev_b32_e32 v214, 16, v92
	v_and_b32_e32 v215, 0xffff0000, v92
	v_exp_f32_e32 v2, v2
	v_mul_f32_e32 v92, 0xbfb8aa3b, v155
	v_lshlrev_b32_e32 v206, 16, v80
	v_and_b32_e32 v207, 0xffff0000, v80
	v_exp_f32_e32 v158, v92
	s_waitcnt vmcnt(2)
	v_pk_fma_f32 v[192:193], v[36:37], v[202:203], 0 op_sel_hi:[1,1,0]
	v_lshlrev_b32_e32 v210, 16, v88
	v_and_b32_e32 v211, 0xffff0000, v88
	s_waitcnt vmcnt(2)
	v_pk_fma_f32 v[192:193], v[44:45], v[206:207], v[192:193]
	v_add_f32_e32 v2, 1.0, v2
	s_waitcnt vmcnt(2)
	v_pk_fma_f32 v[192:193], v[52:53], v[210:211], v[192:193]
	v_rcp_f32_e32 v184, v2
	s_waitcnt vmcnt(2)
	v_pk_fma_f32 v[192:193], v[60:61], v[214:215], v[192:193]
	v_add_f32_e32 v2, 1.0, v158
	v_mul_f32_e32 v158, 0xbfb8aa3b, v192
	v_exp_f32_e32 v158, v158
	v_mul_f32_e32 v159, 0xbfb8aa3b, v193
	v_exp_f32_e32 v159, v159
	v_pk_fma_f32 v[178:179], v[6:7], v[178:179], 0 op_sel_hi:[1,1,0]
	v_lshlrev_b32_e32 v176, 16, v177
	v_pk_fma_f32 v[178:179], v[14:15], v[186:187], v[178:179]
	v_and_b32_e32 v177, 0xffff0000, v177
	v_rcp_f32_e32 v185, v2
	v_add_f32_e32 v2, 1.0, v158
	v_pk_fma_f32 v[178:179], v[22:23], v[194:195], v[178:179]
	v_rcp_f32_e32 v198, v2
	v_add_f32_e32 v2, 1.0, v159
	v_pk_fma_f32 v[176:177], v[30:31], v[176:177], v[178:179]
	v_rcp_f32_e32 v199, v2
	v_mul_f32_e32 v2, 0xbfb8aa3b, v176
	v_exp_f32_e32 v2, v2
	v_mul_f32_e32 v158, 0xbfb8aa3b, v177
	v_exp_f32_e32 v158, v158
	v_pk_fma_f32 v[94:95], v[8:9], v[94:95], 0 op_sel_hi:[1,1,0]
	v_lshlrev_b32_e32 v196, 16, v174
	v_pk_fma_f32 v[94:95], v[16:17], v[180:181], v[94:95]
	v_and_b32_e32 v197, 0xffff0000, v174
	v_add_f32_e32 v2, 1.0, v2
	v_pk_fma_f32 v[94:95], v[24:25], v[188:189], v[94:95]
	v_rcp_f32_e32 v186, v2
	v_add_f32_e32 v2, 1.0, v158
	v_pk_fma_f32 v[94:95], v[32:33], v[196:197], v[94:95]
	v_rcp_f32_e32 v187, v2
	v_mul_f32_e32 v2, 0xbfb8aa3b, v94
	v_exp_f32_e32 v2, v2
	v_mul_f32_e32 v158, 0xbfb8aa3b, v95
	v_exp_f32_e32 v158, v158
	v_pk_fma_f32 v[106:107], v[10:11], v[106:107], 0 op_sel_hi:[1,1,0]
	v_lshlrev_b32_e32 v174, 16, v175
	v_pk_fma_f32 v[106:107], v[18:19], v[182:183], v[106:107]
; __device__ __forceinline__ float bflo(unsigned u) { return __uint_as_float(u << 16); }
; __device__ __forceinline__ float sigmoidf_(float x) { return __builtin_amdgcn_rcpf(1.0f + __expf(-x)); }
; __device__ __forceinline__ float softplusf_(float x) { return fmaxf(x, 0.f) + __logf(1.0f + __expf(-fabsf(x))); }
; __device__ __forceinline__ float red8d(float x) { x += dpp_x1(x); x += dpp_x2(x); x += dpp_hm(x); return x; }
; template <int MIX>
; __device__ __forceinline__ void scan_part(const Params& p, const int layer, const int smp, const int b0, const int bstep, const int bend, const int h, const int part, char* lds, const int tid) {
;     ...
; #pragma unroll
;         for (int i = 0; i < VN; ++i) dst[192 + sub * VN + i] = xv[i];
;         float ssq = 0.f, ssk = 0.f;
; #pragma unroll
;         for (int i = 0; i < 8; ++i) { ssq += xq[i] * xq[i]; ssk += xk[i] * xk[i]; }
;         ssq = red8d(ssq); ssk = red8d(ssk);
;         const float rq = rsqrtf(ssq + 1e-6f) * 0.125f, rk = rsqrtf(ssk + 1e-6f);
;         float qk = 0.f;
; #pragma unroll
;         for (int i = 0; i < 8; ++i) { xq[i] *= rq; xk[i] *= rk; qk += xq[i] * xk[i]; }
;         qk = red8d(qk);
;         *(f32x4*)(dst + sub * 8) = (f32x4){xq[0], xq[1], xq[2], xq[3]}; *(f32x4*)(dst + sub * 8 + 4) = (f32x4){xq[4], xq[5], xq[6], xq[7]};
;         *(f32x4*)(dst + 64 + sub * 8) = (f32x4){xk[0], xk[1], xk[2], xk[3]}; *(f32x4*)(dst + 64 + sub * 8 + 4) = (f32x4){xk[4], xk[5], xk[6], xk[7]};
;         if (sub == 0) {
;           const float be = sigmoidf_(bflo(ex0)), al = bflo(ex1);
;           const float a = __expf(-Aexp * softplusf_(al + dtb));
;           *(f32x4*)(scal + tt * 4) = (f32x4){a, be, qk, 0.f};
;         }
	v_and_b32_e32 v175, 0xffff0000, v175
	v_pk_fma_f32 v[106:107], v[26:27], v[190:191], v[106:107]
	v_add_f32_e32 v2, 1.0, v2
	v_pk_fma_f32 v[106:107], v[34:35], v[174:175], v[106:107]
	v_rcp_f32_e32 v180, v2
	v_add_f32_e32 v2, 1.0, v158
	v_mul_f32_e32 v158, 0xbfb8aa3b, v106
	v_exp_f32_e32 v158, v158
	v_mul_f32_e32 v159, 0xbfb8aa3b, v107
	v_lshlrev_b32_e32 v84, 16, v85
	v_and_b32_e32 v85, 0xffff0000, v85
	v_exp_f32_e32 v159, v159
	v_lshlrev_b32_e32 v80, 16, v81
	v_and_b32_e32 v81, 0xffff0000, v81
	v_pk_fma_f32 v[84:85], v[38:39], v[84:85], 0 op_sel_hi:[1,1,0]
	v_lshlrev_b32_e32 v88, 16, v89
	v_and_b32_e32 v89, 0xffff0000, v89
	v_pk_fma_f32 v[80:81], v[46:47], v[80:81], v[84:85]
	v_lshlrev_b32_e32 v92, 16, v93
	v_and_b32_e32 v93, 0xffff0000, v93
	v_rcp_f32_e32 v181, v2
	v_add_f32_e32 v2, 1.0, v158
	v_pk_fma_f32 v[80:81], v[54:55], v[88:89], v[80:81]
	v_rcp_f32_e32 v174, v2
	v_add_f32_e32 v2, 1.0, v159
	v_pk_fma_f32 v[80:81], v[62:63], v[92:93], v[80:81]
	v_rcp_f32_e32 v175, v2
	v_mul_f32_e32 v2, 0xbfb8aa3b, v80
	v_exp_f32_e32 v2, v2
	v_mul_f32_e32 v84, 0xbfb8aa3b, v81
	v_exp_f32_e32 v89, v84
	v_lshlrev_b32_e32 v200, 16, v82
	v_and_b32_e32 v201, 0xffff0000, v82
	v_lshlrev_b32_e32 v204, 16, v78
	v_and_b32_e32 v205, 0xffff0000, v78
	v_add_f32_e32 v2, 1.0, v2
	v_pk_fma_f32 v[92:93], v[40:41], v[200:201], 0 op_sel_hi:[1,1,0]
	v_lshlrev_b32_e32 v82, 16, v83
	v_and_b32_e32 v83, 0xffff0000, v83
	v_lshlrev_b32_e32 v208, 16, v86
	v_and_b32_e32 v209, 0xffff0000, v86
	v_rcp_f32_e32 v88, v2
	v_add_f32_e32 v2, 1.0, v89
	v_pk_fma_f32 v[92:93], v[48:49], v[204:205], v[92:93]
	v_lshlrev_b32_e32 v78, 16, v79
	v_and_b32_e32 v79, 0xffff0000, v79
	v_lshlrev_b32_e32 v212, 16, v90
	v_and_b32_e32 v213, 0xffff0000, v90
	v_rcp_f32_e32 v89, v2
	v_pk_fma_f32 v[92:93], v[56:57], v[208:209], v[92:93]
	v_pk_fma_f32 v[82:83], v[42:43], v[82:83], 0 op_sel_hi:[1,1,0]
	v_lshlrev_b32_e32 v86, 16, v87
	v_and_b32_e32 v87, 0xffff0000, v87
	s_waitcnt vmcnt(2)
	v_pk_fma_f32 v[92:93], v[64:65], v[212:213], v[92:93]
	v_pk_fma_f32 v[78:79], v[50:51], v[78:79], v[82:83]
	v_lshlrev_b32_e32 v90, 16, v91
	v_and_b32_e32 v91, 0xffff0000, v91
	v_mul_f32_e32 v2, 0xbfb8aa3b, v92
	v_pk_fma_f32 v[78:79], v[58:59], v[86:87], v[78:79]
	v_exp_f32_e32 v2, v2
	v_mul_f32_e32 v158, 0xbfb8aa3b, v93
	v_pk_fma_f32 v[78:79], v[66:67], v[90:91], v[78:79]
	v_pk_mul_f32 v[106:107], v[106:107], v[174:175]
	v_exp_f32_e32 v158, v158
	v_pk_mul_f32 v[174:175], v[80:81], v[88:89]
	v_mul_f32_e32 v81, 0xbfb8aa3b, v78
	v_exp_f32_e32 v82, v81
	v_mul_f32_e32 v81, 0xbfb8aa3b, v79
	v_exp_f32_e32 v83, v81
	v_add_f32_e32 v2, 1.0, v2
	v_rcp_f32_e32 v80, v2
	v_add_f32_e32 v2, 1.0, v158
	v_rcp_f32_e32 v81, v2
	v_add_f32_e32 v2, 1.0, v82
	v_rcp_f32_e32 v82, v2
	v_add_f32_e32 v2, 1.0, v83
	v_rcp_f32_e32 v83, v2
	v_pk_mul_f32 v[94:95], v[94:95], v[180:181]
	v_pk_mul_f32 v[88:89], v[92:93], v[80:81]
	v_pk_mul_f32 v[180:181], v[94:95], v[94:95]
	v_pk_mul_f32 v[80:81], v[88:89], v[88:89]
	v_pk_mul_f32 v[90:91], v[78:79], v[82:83]
	v_pk_mul_f32 v[84:85], v[106:107], v[106:107]
	v_pk_mul_f32 v[78:79], v[90:91], v[90:91]
	v_mov_b32_e32 v82, v80
	v_mov_b32_e32 v83, v180
	v_mov_b32_e32 v180, v81
	v_pk_mul_f32 v[154:155], v[154:155], v[184:185]
	v_pk_mul_f32 v[192:193], v[192:193], v[198:199]
	v_pk_add_f32 v[80:81], v[82:83], v[180:181]
	v_mov_b32_e32 v82, v78
	v_mov_b32_e32 v83, v84
	v_pk_mul_f32 v[184:185], v[154:155], v[154:155]
	v_pk_mul_f32 v[178:179], v[192:193], v[192:193]
	v_pk_add_f32 v[80:81], v[80:81], v[82:83]
	v_mov_b32_e32 v84, v79
	v_pk_mul_f32 v[176:177], v[176:177], v[186:187]
	v_pk_add_f32 v[78:79], v[84:85], v[80:81]
	v_mov_b32_e32 v80, v178
	v_mov_b32_e32 v81, v184
	v_pk_mul_f32 v[182:183], v[176:177], v[176:177]
	v_pk_mul_f32 v[86:87], v[174:175], v[174:175]
	v_pk_add_f32 v[78:79], v[80:81], v[78:79]
	v_mov_b32_e32 v184, v179
	v_pk_add_f32 v[78:79], v[184:185], v[78:79]
	v_mov_b32_e32 v80, v86
	v_mov_b32_e32 v81, v182
	v_pk_add_f32 v[78:79], v[80:81], v[78:79]
	v_mov_b32_e32 v182, v87
	v_pk_add_f32 v[78:79], v[182:183], v[78:79]
	s_mov_b32 s44, 0x358637bd
	v_pk_mul_f32 v[0:1], v[0:1], v[76:77]
	v_mov_b32_dpp v81, v79 quad_perm:[1,0,3,2] row_mask:0xf bank_mask:0xf bound_ctrl:1
	v_mov_b32_dpp v80, v78 quad_perm:[1,0,3,2] row_mask:0xf bank_mask:0xf bound_ctrl:1
	v_pk_add_f32 v[78:79], v[78:79], v[80:81]
	ds_write_b64 v141, v[0:1] offset:768
	s_nop 0
	v_mov_b32_dpp v81, v79 quad_perm:[2,3,0,1] row_mask:0xf bank_mask:0xf bound_ctrl:1
	v_mov_b32_dpp v80, v78 quad_perm:[2,3,0,1] row_mask:0xf bank_mask:0xf bound_ctrl:1
	v_pk_add_f32 v[78:79], v[78:79], v[80:81]
	s_nop 1
	v_mov_b32_dpp v81, v79 row_half_mirror row_mask:0xf bank_mask:0xf bound_ctrl:1
	v_mov_b32_dpp v80, v78 row_half_mirror row_mask:0xf bank_mask:0xf bound_ctrl:1
	v_pk_add_f32 v[78:79], v[78:79], v[80:81]
	s_nop 0
	v_pk_add_f32 v[78:79], v[78:79], s[44:45] op_sel_hi:[1,0]
	s_nop 0
	v_mul_f32_e32 v2, 0x4b800000, v79
	v_cmp_gt_f32_e32 vcc, s92, v79
	s_nop 1
	v_cndmask_b32_e32 v2, v79, v2, vcc
	v_rsq_f32_e32 v2, v2
	s_nop 0
	v_mul_f32_e32 v0, 0x45800000, v2
	v_cndmask_b32_e32 v0, v2, v0, vcc
	v_mul_f32_e32 v0, 0x3e000000, v0
	v_pk_mul_f32 v[76:77], v[94:95], v[0:1] op_sel_hi:[1,0]
	v_mul_f32_e32 v1, 0x4b800000, v78
	v_cmp_gt_f32_e32 vcc, s92, v78
	s_nop 1
	v_cndmask_b32_e32 v1, v78, v1, vcc
	v_rsq_f32_e32 v1, v1
	s_nop 0
	v_pk_mul_f32 v[78:79], v[106:107], v[0:1] op_sel_hi:[1,0]
	v_pk_mul_f32 v[80:81], v[154:155], v[0:1] op_sel_hi:[1,0]
	v_pk_mul_f32 v[82:83], v[176:177], v[0:1] op_sel_hi:[1,0]
	v_mul_f32_e32 v0, 0x45800000, v1
	v_cndmask_b32_e32 v0, v1, v0, vcc
	v_pk_mul_f32 v[84:85], v[88:89], v[0:1] op_sel_hi:[1,0]
	s_nop 0
	v_pk_mul_f32 v[86:87], v[90:91], v[0:1] op_sel_hi:[1,0]
	s_nop 0
	v_pk_mul_f32 v[88:89], v[192:193], v[0:1] op_sel_hi:[1,0]
	s_nop 0
	v_pk_mul_f32 v[90:91], v[174:175], v[0:1] op_sel_hi:[1,0]
	ds_write_b128 v152, v[76:79]
	ds_write_b128 v152, v[80:83] offset:16
	ds_write_b128 v152, v[84:87] offset:256
	ds_write_b128 v152, v[88:91] offset:272
	s_and_b64 exec, exec, s[38:39]
	s_cbranch_execz .LBB0_426
	v_mov_b32_e32 v2, 0
	s_waitcnt lgkmcnt(5)
	v_mov_b32_e32 v0, v230
	v_mov_b32_e32 v1, v231
	ds_write_b128 v142, v[0:3] offset:36864
